# attention unit: epilogue gate loads issued in the tile loop's last iteration, before the loop-exit barrier
# speedup vs baseline: 1.0229x; 1.0032x over previous
.LBB0_1053:
	ds_bpermute_b32 v0, v146, v148
	s_lshl_b32 s68, s17, 7
	v_lshlrev_b32_e32 v10, 3, v132
	v_mov_b32_e32 v11, v4
	s_waitcnt lgkmcnt(0)
	v_add_f32_e32 v0, v148, v0
	v_div_scale_f32 v1, s[0:1], v0, v0, 1.0
	v_rcp_f32_e32 v2, v1
	s_add_i32 s0, s19, s18
	v_fma_f32 v3, -v1, v2, 1.0
	v_fmac_f32_e32 v2, v3, v2
	v_div_scale_f32 v3, vcc, 1.0, v0, 1.0
	v_mul_f32_e32 v5, v3, v2
	v_fma_f32 v6, -v1, v5, v3
	v_fmac_f32_e32 v5, v6, v2
	v_fma_f32 v1, -v1, v5, v3
	v_div_fmas_f32 v1, v1, v2, v5
	v_add_u32_e32 v2, s0, v133
	v_ashrrev_i32_e32 v3, 31, v2
	v_mov_b64_e32 v[6:7], s[26:27]
	v_mad_i64_i32 v[8:9], s[0:1], v2, s92, v[6:7]
	v_lshlrev_b64 v[2:3], 9, v[2:3]
	v_sub_co_u32_e32 v2, vcc, 0, v2
	v_lshl_add_u64 v[6:7], v[8:9], 0, s[68:69]
	s_nop 0
	v_subb_co_u32_e32 v3, vcc, 0, v3, vcc
	v_lshl_add_u64 v[2:3], v[8:9], 0, v[2:3]
	v_lshl_add_u64 v[12:13], v[6:7], 0, v[10:11]
	s_mov_b64 s[0:1], 0x4512600
	v_lshl_add_u64 v[2:3], v[2:3], 0, s[68:69]
	v_lshl_add_u64 v[6:7], v[12:13], 0, s[0:1]
	v_lshl_add_u64 v[8:9], v[2:3], 0, v[10:11]
	s_mov_b64 s[0:1], 0x6d12400
	v_lshl_add_u64 v[2:3], v[8:9], 0, s[0:1]
	v_div_fixup_f32 v0, v1, v0, 1.0
	v_lshlrev_b32_e32 v10, 3, v132
	v_mov_b32_e32 v11, v4
	v_lshl_add_u64 v[2:3], v[2:3], 0, v[10:11]
	s_waitcnt vmcnt(3)
	v_permlane32_swap_b32_e32 v48, v50
	v_permlane32_swap_b32_e32 v49, v51
	v_pk_mul_f32 v[12:13], v[32:33], v[0:1] op_sel_hi:[1,0]
	v_lshlrev_b32_e32 v14, 16, v48
	v_and_b32_e32 v15, 0xffff0000, v48
	v_pk_mul_f32 v[12:13], v[12:13], v[14:15]
	v_pk_mul_f32 v[8:9], v[34:35], v[0:1] op_sel_hi:[1,0]
	v_cvt_pk_bf16_f32 v166, v12, v13
	v_lshlrev_b32_e32 v14, 16, v49
	v_and_b32_e32 v15, 0xffff0000, v49
	v_pk_mul_f32 v[8:9], v[8:9], v[14:15]
	s_nop 0
	v_cvt_pk_bf16_f32 v167, v8, v9
	v_pk_mul_f32 v[12:13], v[36:37], v[0:1] op_sel_hi:[1,0]
	v_lshlrev_b32_e32 v14, 16, v50
	v_and_b32_e32 v15, 0xffff0000, v50
	v_pk_mul_f32 v[12:13], v[12:13], v[14:15]
	v_pk_mul_f32 v[8:9], v[38:39], v[0:1] op_sel_hi:[1,0]
	v_cvt_pk_bf16_f32 v168, v12, v13
	v_lshlrev_b32_e32 v14, 16, v51
	v_and_b32_e32 v15, 0xffff0000, v51
	v_pk_mul_f32 v[8:9], v[8:9], v[14:15]
	s_nop 0
	v_cvt_pk_bf16_f32 v169, v8, v9
	s_nop 1
	v_permlane32_swap_b32_e32 v166, v168
	v_permlane32_swap_b32_e32 v167, v169
	global_store_dwordx4 v[2:3], v[166:169], off
	s_waitcnt vmcnt(3)
	v_permlane32_swap_b32_e32 v52, v54
	v_permlane32_swap_b32_e32 v53, v55
	v_pk_mul_f32 v[12:13], v[40:41], v[0:1] op_sel_hi:[1,0]
	v_lshlrev_b32_e32 v14, 16, v52
	v_and_b32_e32 v15, 0xffff0000, v52
	v_pk_mul_f32 v[12:13], v[12:13], v[14:15]
	v_pk_mul_f32 v[8:9], v[42:43], v[0:1] op_sel_hi:[1,0]
	v_cvt_pk_bf16_f32 v170, v12, v13
	v_lshlrev_b32_e32 v14, 16, v53
	v_and_b32_e32 v15, 0xffff0000, v53
	v_pk_mul_f32 v[8:9], v[8:9], v[14:15]
	s_nop 0
	v_cvt_pk_bf16_f32 v171, v8, v9
	v_pk_mul_f32 v[12:13], v[44:45], v[0:1] op_sel_hi:[1,0]
	v_lshlrev_b32_e32 v14, 16, v54
	v_and_b32_e32 v15, 0xffff0000, v54
	v_pk_mul_f32 v[12:13], v[12:13], v[14:15]
	v_pk_mul_f32 v[8:9], v[46:47], v[0:1] op_sel_hi:[1,0]
	v_cvt_pk_bf16_f32 v172, v12, v13
	v_lshlrev_b32_e32 v14, 16, v55
	v_and_b32_e32 v15, 0xffff0000, v55
	v_pk_mul_f32 v[8:9], v[8:9], v[14:15]
	s_nop 0
	v_cvt_pk_bf16_f32 v173, v8, v9
	s_nop 1
	v_permlane32_swap_b32_e32 v170, v172
	v_permlane32_swap_b32_e32 v171, v173
	global_store_dwordx4 v[2:3], v[170:173], off offset:32
	s_waitcnt vmcnt(3)
	v_permlane32_swap_b32_e32 v56, v58
	v_permlane32_swap_b32_e32 v57, v59
	v_pk_mul_f32 v[12:13], v[16:17], v[0:1] op_sel_hi:[1,0]
	v_lshlrev_b32_e32 v14, 16, v56
	v_and_b32_e32 v15, 0xffff0000, v56
	v_pk_mul_f32 v[12:13], v[12:13], v[14:15]
	v_pk_mul_f32 v[8:9], v[18:19], v[0:1] op_sel_hi:[1,0]
	v_cvt_pk_bf16_f32 v174, v12, v13
	v_lshlrev_b32_e32 v14, 16, v57
	v_and_b32_e32 v15, 0xffff0000, v57
	v_pk_mul_f32 v[8:9], v[8:9], v[14:15]
	s_nop 0
	v_cvt_pk_bf16_f32 v175, v8, v9
	v_pk_mul_f32 v[12:13], v[20:21], v[0:1] op_sel_hi:[1,0]
	v_lshlrev_b32_e32 v14, 16, v58
	v_and_b32_e32 v15, 0xffff0000, v58
	v_pk_mul_f32 v[12:13], v[12:13], v[14:15]
	v_pk_mul_f32 v[8:9], v[22:23], v[0:1] op_sel_hi:[1,0]
	v_cvt_pk_bf16_f32 v176, v12, v13
	v_lshlrev_b32_e32 v14, 16, v59
	v_and_b32_e32 v15, 0xffff0000, v59
	v_pk_mul_f32 v[8:9], v[8:9], v[14:15]
	s_nop 0
	v_cvt_pk_bf16_f32 v177, v8, v9
	s_nop 1
	v_permlane32_swap_b32_e32 v174, v176
	v_permlane32_swap_b32_e32 v175, v177
	global_store_dwordx4 v[2:3], v[174:177], off offset:64
	s_waitcnt vmcnt(3)
	v_permlane32_swap_b32_e32 v60, v62
	v_permlane32_swap_b32_e32 v61, v63
	v_pk_mul_f32 v[12:13], v[24:25], v[0:1] op_sel_hi:[1,0]
	v_lshlrev_b32_e32 v14, 16, v60
	v_and_b32_e32 v15, 0xffff0000, v60
	v_pk_mul_f32 v[12:13], v[12:13], v[14:15]
	v_pk_mul_f32 v[8:9], v[26:27], v[0:1] op_sel_hi:[1,0]
	v_cvt_pk_bf16_f32 v178, v12, v13
	v_lshlrev_b32_e32 v14, 16, v61
	v_and_b32_e32 v15, 0xffff0000, v61
	v_pk_mul_f32 v[8:9], v[8:9], v[14:15]
	s_nop 0
	v_cvt_pk_bf16_f32 v179, v8, v9
	v_pk_mul_f32 v[12:13], v[28:29], v[0:1] op_sel_hi:[1,0]
	v_lshlrev_b32_e32 v14, 16, v62
	v_and_b32_e32 v15, 0xffff0000, v62
	v_pk_mul_f32 v[12:13], v[12:13], v[14:15]
	v_pk_mul_f32 v[8:9], v[30:31], v[0:1] op_sel_hi:[1,0]
	v_cvt_pk_bf16_f32 v180, v12, v13
	v_lshlrev_b32_e32 v14, 16, v63
	v_and_b32_e32 v15, 0xffff0000, v63
	v_pk_mul_f32 v[8:9], v[8:9], v[14:15]
	s_nop 0
	v_cvt_pk_bf16_f32 v181, v8, v9
	s_nop 1
	v_permlane32_swap_b32_e32 v178, v180
	v_permlane32_swap_b32_e32 v179, v181
	global_store_dwordx4 v[2:3], v[178:181], off offset:96

.LBB0_1170:
	s_add_u32 s14, s14, 0x2000
	s_addc_u32 s15, s15, 0
	s_add_u32 s12, s12, 0x4000
	s_addc_u32 s13, s13, 0
	s_add_i32 s22, s22, 2
	s_cmp_lt_u32 s23, s16
	s_cbranch_scc1 .Lgate_pf_skip
	s_add_i32 s70, s19, s18
	s_mul_i32 s70, s70, 0xa00
	s_lshl_b32 s71, s17, 7
	s_add_u32 s70, s70, s71
	s_add_u32 s70, s70, 0x4512600
	s_add_u32 s72, s26, s70
	s_addc_u32 s73, s27, 0
	v_lshlrev_b32_e32 v65, 4, v132
	v_mad_u32_u24 v64, v133, s92, v65
	global_load_dwordx4 v[48:51], v64, s[72:73]
	global_load_dwordx4 v[52:55], v64, s[72:73] offset:32
	global_load_dwordx4 v[56:59], v64, s[72:73] offset:64
	global_load_dwordx4 v[60:63], v64, s[72:73] offset:96
	s_cmp_lt_u32 s23, s16
.Lgate_pf_skip:
	v_lshl_add_u64 v[130:131], v[130:131], 0, s[96:97]
	s_waitcnt lgkmcnt(0)
	s_barrier
	s_cbranch_scc0 .LBB0_1053
